# qg image assembled in LDS and written as whole lines; roles 1-3 leave their step-4 operand loads in flight across the step-1 barrier
# baseline (speedup 1.0000x reference)
; __device__ __forceinline__ void phase_prep(const Args& a, PG8_LAS unsigned char* lds) {
;     ...
;         if (role != 0) {
; #pragma unroll
;         for (int cc = 0; cc < 2; ++cc) { const int ct = 2 * lw + cc;
;             pv[cc][0] = *(const bf16x8*)(vTb + (size_t)(16 * ct + r) * 64 + 8 * q); pv[cc][1] = *(const bf16x8*)(vTb + (size_t)(16 * ct + r) * 64 + 32 + 8 * q);
;             pk[cc][0] = *(const bf16x8*)(kTb + (size_t)(16 * ct + r) * 64 + 8 * q); pk[cc][1] = *(const bf16x8*)(kTb + (size_t)(16 * ct + r) * 64 + 32 + 8 * q); } }
;         float gv = gB[(r0 + lane) * 4 + h];
; #pragma unroll
;         for (int off = 1; off < 64; off <<= 1) { const float t = __shfl_up(gv, off); if (lane >= off) gv += t; }
;         const float g63 = __shfl(gv, 63);
;         if (lw == 0) { sG[lane] = gv; sB[lane] = betaB[(r0 + lane) * 4 + h]; sE[lane] = __expf(gv); sK[lane] = __expf(g63 - gv); }
;         if ((tid & 255) == 0) glast[item] = __expf(g63);
;         __syncthreads();
.LBB0_259:
	s_or_b64 exec, exec, s[26:27]
	v_readlane_b32 s40, v253, 53
	v_readlane_b32 s41, v253, 54
	s_andn2_b64 vcc, exec, s[40:41]
	s_cbranch_vccnz .Lpp_w0
	s_waitcnt vmcnt(8)
	s_branch .Lpp_w1

; #define MFMA16(a, b, c) __builtin_amdgcn_mfma_f32_16x16x32_bf16((a), (b), (c), 0, 0, 0)
; __device__ __forceinline__ void phase_prep(const Args& a, PG8_LAS unsigned char* lds) {
;     ...
;         __syncthreads();
;         {
; #pragma unroll
;             for (int tj = 0; tj < 4; ++tj) {
;                 f32x4 ckk = {0.f, 0.f, 0.f, 0.f}, cqk = {0.f, 0.f, 0.f, 0.f};
; #pragma unroll
;                 for (int s = 0; s < 4; ++s) { const bf16x8 bk = (tj < 2) ? bkf[tj & 1][s] : *(const bf16x8*)(kbase + (size_t)(16 * tj + r) * 512 + 32 * s + 8 * q); ckk = MFMA16(ak[s], bk, ckk); cqk = MFMA16(aq[s], bk, cqk); }
;                 const int j = 16 * tj + r; const float Gj = sG[j]; const int jpos = (j & 32) + perm32s(j & 31);
;                 f32x4 lv;
; #pragma unroll
;                 for (int e = 0; e < 4; ++e) { const int i = 16 * lw + 4 * q + e; const float Gi = sG[i], bi = sB[i];
;                     const float dec = (i >= j) ? __expf(Gi - Gj) : 0.f;
.Lpp_w1:
	v_mfma_f32_16x16x32_bf16 v[230:233], v[56:59], v[92:95], 0
	s_waitcnt lgkmcnt(0)
	s_barrier
	v_mfma_f32_16x16x32_bf16 v[92:95], v[60:63], v[92:95], 0
	v_readlane_b32 s40, v252, 5
	v_readlane_b32 s41, v252, 6
	v_mfma_f32_16x16x32_bf16 v[230:233], v[48:51], v[88:91], v[230:233]
	v_mfma_f32_16x16x32_bf16 v[88:91], v[52:55], v[88:91], v[92:95]
	v_mfma_f32_16x16x32_bf16 v[92:95], v[40:43], v[84:87], v[230:233]
	v_mfma_f32_16x16x32_bf16 v[230:233], v[44:47], v[84:87], v[88:91]
	s_nop 5
	ds_read_b32 v90, v137
	ds_read_b32 v89, v138 offset:256
	v_mov_b32_e32 v88, 0
	v_mov_b32_e32 v91, 0
	v_mfma_f32_16x16x32_bf16 v[84:87], v[32:35], v[80:83], v[92:95]
	v_mfma_f32_16x16x32_bf16 v[80:83], v[36:39], v[80:83], v[230:233]
	s_and_saveexec_b64 s[26:27], s[40:41]
	s_cbranch_execz .LBB0_261
	ds_read_b32 v91, v138
	s_waitcnt lgkmcnt(0)
	v_sub_f32_e32 v91, v91, v90
	v_mul_f32_e32 v91, 0x3fb8aa3b, v91
	v_exp_f32_e32 v91, v91

; __device__ __forceinline__ unsigned pk2(float a, float b) { return pg8::cvt_pk_bf16(a, b); }
; __device__ __forceinline__ void unpack8(const u32x4 w, float (&f)[8]) { f[0] = bf_lo(w.x); f[1] = bf_hi(w.x); f[2] = bf_lo(w.y); f[3] = bf_hi(w.y); f[4] = bf_lo(w.z); f[5] = bf_hi(w.z); f[6] = bf_lo(w.w); f[7] = bf_hi(w.w); }
; __device__ __forceinline__ void phase_prep(const Args& a, PG8_LAS unsigned char* lds) {
;     ...
; #pragma unroll 4
;             for (int k = 0; k < 16; ++k) { const int pidx = lane + 64 * k, i = pidx >> 4, pc = pidx & 15, aa = pc & 3, c32 = (pc >> 2) * 32;
;                 float f[8]; unpack8(*(const u32x4*)(qbase + (size_t)i * 512 + pc * 8), f); const float e = sE[i];
;                 u32x2 lo, hi; lo.x = pk2(f[0] * e, f[1] * e); lo.y = pk2(f[2] * e, f[3] * e); hi.x = pk2(f[4] * e, f[5] * e); hi.y = pk2(f[6] * e, f[7] * e);
;                 *(u32x2*)(qgp + i * 128 + c32 + 8 * ((2 * aa) & 3) + 4 * (aa >> 1)) = lo;
;                 *(u32x2*)(qgp + i * 128 + c32 + 8 * ((2 * aa + 1) & 3) + 4 * (aa >> 1)) = hi; }
.LBB0_296:
	v_lshl_add_u64 v[40:41], s[16:17], 0, v[32:33]
	v_add_co_u32_e32 v40, vcc, 0x10001000, v40
	s_nop 1
	v_addc_co_u32_e32 v41, vcc, 0, v41, vcc
	v_lshl_add_u64 v[42:43], s[16:17], 0, v[34:35]
	s_mov_b64 s[24:25], 0x2000
	v_and_b32_e32 v36, 63, v152
	v_lshrrev_b32_e32 v37, 4, v36
	v_lshlrev_b32_e32 v37, 8, v37
	v_bfe_u32 v38, v36, 2, 2
	v_lshl_add_u32 v37, v38, 6, v37
	v_and_b32_e32 v38, 1, v36
	v_lshl_add_u32 v37, v38, 5, v37
	v_bfe_u32 v38, v36, 1, 1
	v_lshl_add_u32 v37, v38, 3, v37
	v_lshlrev_b32_e32 v36, 4, v36
	v_readfirstlane_b32 s26, v152
	s_lshr_b32 s26, s26, 8
	s_lshl_b32 s26, s26, 14
	s_add_u32 s26, s26, 0x12000
	v_add_u32_e32 v38, s26, v37
	v_add_u32_e32 v39, s26, v36
	v_sub_u32_e32 v36, v36, v37
	v_add_u32_e32 v36, 0xfffff800, v36
	v_ashrrev_i32_e32 v37, 31, v36
	v_lshl_add_u64 v[42:43], v[42:43], 0, v[36:37]
	ds_read_b32 v84, v206
	ds_read_b32 v85, v206 offset:16
	ds_read_b32 v86, v206 offset:32
	ds_read_b32 v87, v206 offset:48
	ds_read_b32 v88, v206 offset:64
	ds_read_b32 v89, v206 offset:80
	ds_read_b32 v90, v206 offset:96
	ds_read_b32 v91, v206 offset:112
	ds_read_b32 v92, v206 offset:128
	ds_read_b32 v93, v206 offset:144
	ds_read_b32 v94, v206 offset:160
	ds_read_b32 v95, v206 offset:176
	ds_read_b32 v44, v206 offset:192
	ds_read_b32 v45, v206 offset:208
	ds_read_b32 v46, v206 offset:224
	ds_read_b32 v47, v206 offset:240
	global_load_dwordx4 v[52:55], v[40:41], off offset:-4096
	global_load_dwordx4 v[56:59], v[40:41], off
	v_lshl_add_u64 v[40:41], v[40:41], 0, s[24:25]
	global_load_dwordx4 v[60:63], v[40:41], off offset:-4096
	global_load_dwordx4 v[64:67], v[40:41], off
	v_lshl_add_u64 v[40:41], v[40:41], 0, s[24:25]
	global_load_dwordx4 v[68:71], v[40:41], off offset:-4096
	global_load_dwordx4 v[72:75], v[40:41], off
	v_lshl_add_u64 v[40:41], v[40:41], 0, s[24:25]
	global_load_dwordx4 v[76:79], v[40:41], off offset:-4096
	global_load_dwordx4 v[80:83], v[40:41], off
	v_lshl_add_u64 v[40:41], v[40:41], 0, s[24:25]
	s_waitcnt lgkmcnt(0)
	s_waitcnt vmcnt(7)
	v_lshlrev_b32_e32 v48, 16, v52
	v_and_b32_e32 v52, 0xffff0000, v52
	v_lshlrev_b32_e32 v49, 16, v53
	v_and_b32_e32 v53, 0xffff0000, v53
	v_lshlrev_b32_e32 v50, 16, v54
	v_and_b32_e32 v54, 0xffff0000, v54
	v_lshlrev_b32_e32 v51, 16, v55
	v_and_b32_e32 v55, 0xffff0000, v55
	v_mul_f32_e32 v52, v84, v52
	v_mul_f32_e32 v48, v84, v48
	v_mul_f32_e32 v53, v84, v53
	v_mul_f32_e32 v49, v84, v49
	v_mul_f32_e32 v54, v84, v54
	v_mul_f32_e32 v50, v84, v50
	v_mul_f32_e32 v55, v84, v55
	v_mul_f32_e32 v51, v84, v51
	v_cvt_pk_bf16_f32 v52, v48, v52
	v_cvt_pk_bf16_f32 v53, v49, v53
	v_cvt_pk_bf16_f32 v54, v50, v54
	v_cvt_pk_bf16_f32 v55, v51, v55
	s_nop 0
	ds_write_b64 v38, v[52:53]
	ds_write_b64 v38, v[54:55] offset:16
	global_load_dwordx4 v[52:55], v[40:41], off offset:-4096
	s_waitcnt vmcnt(7)
	v_lshlrev_b32_e32 v48, 16, v56
	v_and_b32_e32 v56, 0xffff0000, v56
	v_lshlrev_b32_e32 v49, 16, v57
	v_and_b32_e32 v57, 0xffff0000, v57
	v_lshlrev_b32_e32 v50, 16, v58
	v_and_b32_e32 v58, 0xffff0000, v58
	v_lshlrev_b32_e32 v51, 16, v59
	v_and_b32_e32 v59, 0xffff0000, v59
	v_mul_f32_e32 v56, v85, v56
	v_mul_f32_e32 v48, v85, v48
	v_mul_f32_e32 v57, v85, v57
	v_mul_f32_e32 v49, v85, v49
	v_mul_f32_e32 v58, v85, v58
	v_mul_f32_e32 v50, v85, v50
	v_mul_f32_e32 v59, v85, v59
	v_mul_f32_e32 v51, v85, v51
	v_cvt_pk_bf16_f32 v56, v48, v56
	v_cvt_pk_bf16_f32 v57, v49, v57
	v_cvt_pk_bf16_f32 v58, v50, v58
	v_cvt_pk_bf16_f32 v59, v51, v59
	s_nop 0
	ds_write_b64 v38, v[56:57] offset:1024
	ds_write_b64 v38, v[58:59] offset:1040
	global_load_dwordx4 v[56:59], v[40:41], off
	v_lshl_add_u64 v[40:41], v[40:41], 0, s[24:25]
	s_waitcnt vmcnt(7)
	v_lshlrev_b32_e32 v48, 16, v60
	v_and_b32_e32 v60, 0xffff0000, v60
	v_lshlrev_b32_e32 v49, 16, v61
	v_and_b32_e32 v61, 0xffff0000, v61
	v_lshlrev_b32_e32 v50, 16, v62
	v_and_b32_e32 v62, 0xffff0000, v62
	v_lshlrev_b32_e32 v51, 16, v63
	v_and_b32_e32 v63, 0xffff0000, v63
	v_mul_f32_e32 v60, v86, v60
	v_mul_f32_e32 v48, v86, v48
	v_mul_f32_e32 v61, v86, v61
	v_mul_f32_e32 v49, v86, v49
	v_mul_f32_e32 v62, v86, v62
	v_mul_f32_e32 v50, v86, v50
	v_mul_f32_e32 v63, v86, v63
	v_mul_f32_e32 v51, v86, v51
	v_cvt_pk_bf16_f32 v60, v48, v60
	v_cvt_pk_bf16_f32 v61, v49, v61
	v_cvt_pk_bf16_f32 v62, v50, v62
	v_cvt_pk_bf16_f32 v63, v51, v63
	s_nop 0
	ds_write_b64 v38, v[60:61] offset:2048
	ds_write_b64 v38, v[62:63] offset:2064
	global_load_dwordx4 v[60:63], v[40:41], off offset:-4096
	s_waitcnt vmcnt(7)
	v_lshlrev_b32_e32 v48, 16, v64
	v_and_b32_e32 v64, 0xffff0000, v64
	v_lshlrev_b32_e32 v49, 16, v65
	v_and_b32_e32 v65, 0xffff0000, v65
	v_lshlrev_b32_e32 v50, 16, v66
	v_and_b32_e32 v66, 0xffff0000, v66
	v_lshlrev_b32_e32 v51, 16, v67
	v_and_b32_e32 v67, 0xffff0000, v67
	v_mul_f32_e32 v64, v87, v64
	v_mul_f32_e32 v48, v87, v48
	v_mul_f32_e32 v65, v87, v65
	v_mul_f32_e32 v49, v87, v49
	v_mul_f32_e32 v66, v87, v66
	v_mul_f32_e32 v50, v87, v50
	v_mul_f32_e32 v67, v87, v67
	v_mul_f32_e32 v51, v87, v51
	v_cvt_pk_bf16_f32 v64, v48, v64
	v_cvt_pk_bf16_f32 v65, v49, v65
	v_cvt_pk_bf16_f32 v66, v50, v66
	v_cvt_pk_bf16_f32 v67, v51, v67
	s_nop 0
	ds_write_b64 v38, v[64:65] offset:3072
	ds_write_b64 v38, v[66:67] offset:3088
	global_load_dwordx4 v[64:67], v[40:41], off
	v_lshl_add_u64 v[40:41], v[40:41], 0, s[24:25]
	s_waitcnt vmcnt(7)
; __device__ __forceinline__ unsigned pk2(float a, float b) { return pg8::cvt_pk_bf16(a, b); }
; __device__ __forceinline__ void unpack8(const u32x4 w, float (&f)[8]) { f[0] = bf_lo(w.x); f[1] = bf_hi(w.x); f[2] = bf_lo(w.y); f[3] = bf_hi(w.y); f[4] = bf_lo(w.z); f[5] = bf_hi(w.z); f[6] = bf_lo(w.w); f[7] = bf_hi(w.w); }
; __device__ __forceinline__ void phase_prep(const Args& a, PG8_LAS unsigned char* lds) {
;     ...
; #pragma unroll 4
;             for (int k = 0; k < 16; ++k) { const int pidx = lane + 64 * k, i = pidx >> 4, pc = pidx & 15, aa = pc & 3, c32 = (pc >> 2) * 32;
;                 float f[8]; unpack8(*(const u32x4*)(qbase + (size_t)i * 512 + pc * 8), f); const float e = sE[i];
;                 u32x2 lo, hi; lo.x = pk2(f[0] * e, f[1] * e); lo.y = pk2(f[2] * e, f[3] * e); hi.x = pk2(f[4] * e, f[5] * e); hi.y = pk2(f[6] * e, f[7] * e);
;                 *(u32x2*)(qgp + i * 128 + c32 + 8 * ((2 * aa) & 3) + 4 * (aa >> 1)) = lo;
;                 *(u32x2*)(qgp + i * 128 + c32 + 8 * ((2 * aa + 1) & 3) + 4 * (aa >> 1)) = hi; }
	v_lshlrev_b32_e32 v48, 16, v68
	v_and_b32_e32 v68, 0xffff0000, v68
	v_lshlrev_b32_e32 v49, 16, v69
	v_and_b32_e32 v69, 0xffff0000, v69
	v_lshlrev_b32_e32 v50, 16, v70
	v_and_b32_e32 v70, 0xffff0000, v70
	v_lshlrev_b32_e32 v51, 16, v71
	v_and_b32_e32 v71, 0xffff0000, v71
	v_mul_f32_e32 v68, v88, v68
	v_mul_f32_e32 v48, v88, v48
	v_mul_f32_e32 v69, v88, v69
	v_mul_f32_e32 v49, v88, v49
	v_mul_f32_e32 v70, v88, v70
	v_mul_f32_e32 v50, v88, v50
	v_mul_f32_e32 v71, v88, v71
	v_mul_f32_e32 v51, v88, v51
	v_cvt_pk_bf16_f32 v68, v48, v68
	v_cvt_pk_bf16_f32 v69, v49, v69
	v_cvt_pk_bf16_f32 v70, v50, v70
	v_cvt_pk_bf16_f32 v71, v51, v71
	s_nop 0
	ds_write_b64 v38, v[68:69] offset:4096
	ds_write_b64 v38, v[70:71] offset:4112
	global_load_dwordx4 v[68:71], v[40:41], off offset:-4096
	s_waitcnt vmcnt(7)
	v_lshlrev_b32_e32 v48, 16, v72
	v_and_b32_e32 v72, 0xffff0000, v72
	v_lshlrev_b32_e32 v49, 16, v73
	v_and_b32_e32 v73, 0xffff0000, v73
	v_lshlrev_b32_e32 v50, 16, v74
	v_and_b32_e32 v74, 0xffff0000, v74
	v_lshlrev_b32_e32 v51, 16, v75
	v_and_b32_e32 v75, 0xffff0000, v75
	v_mul_f32_e32 v72, v89, v72
	v_mul_f32_e32 v48, v89, v48
	v_mul_f32_e32 v73, v89, v73
	v_mul_f32_e32 v49, v89, v49
	v_mul_f32_e32 v74, v89, v74
	v_mul_f32_e32 v50, v89, v50
	v_mul_f32_e32 v75, v89, v75
	v_mul_f32_e32 v51, v89, v51
	v_cvt_pk_bf16_f32 v72, v48, v72
	v_cvt_pk_bf16_f32 v73, v49, v73
	v_cvt_pk_bf16_f32 v74, v50, v74
	v_cvt_pk_bf16_f32 v75, v51, v75
	s_nop 0
	ds_write_b64 v38, v[72:73] offset:5120
	ds_write_b64 v38, v[74:75] offset:5136
	global_load_dwordx4 v[72:75], v[40:41], off
	v_lshl_add_u64 v[40:41], v[40:41], 0, s[24:25]
	s_waitcnt vmcnt(7)
	v_lshlrev_b32_e32 v48, 16, v76
	v_and_b32_e32 v76, 0xffff0000, v76
	v_lshlrev_b32_e32 v49, 16, v77
	v_and_b32_e32 v77, 0xffff0000, v77
	v_lshlrev_b32_e32 v50, 16, v78
	v_and_b32_e32 v78, 0xffff0000, v78
	v_lshlrev_b32_e32 v51, 16, v79
	v_and_b32_e32 v79, 0xffff0000, v79
	v_mul_f32_e32 v76, v90, v76
	v_mul_f32_e32 v48, v90, v48
	v_mul_f32_e32 v77, v90, v77
	v_mul_f32_e32 v49, v90, v49
	v_mul_f32_e32 v78, v90, v78
	v_mul_f32_e32 v50, v90, v50
	v_mul_f32_e32 v79, v90, v79
	v_mul_f32_e32 v51, v90, v51
	v_cvt_pk_bf16_f32 v76, v48, v76
	v_cvt_pk_bf16_f32 v77, v49, v77
	v_cvt_pk_bf16_f32 v78, v50, v78
	v_cvt_pk_bf16_f32 v79, v51, v79
	s_nop 0
	ds_write_b64 v38, v[76:77] offset:6144
	ds_write_b64 v38, v[78:79] offset:6160
	global_load_dwordx4 v[76:79], v[40:41], off offset:-4096
	s_waitcnt vmcnt(7)
	v_lshlrev_b32_e32 v48, 16, v80
	v_and_b32_e32 v80, 0xffff0000, v80
	v_lshlrev_b32_e32 v49, 16, v81
	v_and_b32_e32 v81, 0xffff0000, v81
	v_lshlrev_b32_e32 v50, 16, v82
	v_and_b32_e32 v82, 0xffff0000, v82
	v_lshlrev_b32_e32 v51, 16, v83
	v_and_b32_e32 v83, 0xffff0000, v83
	v_mul_f32_e32 v80, v91, v80
	v_mul_f32_e32 v48, v91, v48
	v_mul_f32_e32 v81, v91, v81
	v_mul_f32_e32 v49, v91, v49
	v_mul_f32_e32 v82, v91, v82
	v_mul_f32_e32 v50, v91, v50
	v_mul_f32_e32 v83, v91, v83
	v_mul_f32_e32 v51, v91, v51
	v_cvt_pk_bf16_f32 v80, v48, v80
	v_cvt_pk_bf16_f32 v81, v49, v81
	v_cvt_pk_bf16_f32 v82, v50, v82
	v_cvt_pk_bf16_f32 v83, v51, v83
	s_nop 0
	ds_write_b64 v38, v[80:81] offset:7168
	ds_write_b64 v38, v[82:83] offset:7184
	global_load_dwordx4 v[80:83], v[40:41], off
	v_lshl_add_u64 v[40:41], v[40:41], 0, s[24:25]
	s_waitcnt vmcnt(7)
	v_lshlrev_b32_e32 v48, 16, v52
	v_and_b32_e32 v52, 0xffff0000, v52
	v_lshlrev_b32_e32 v49, 16, v53
	v_and_b32_e32 v53, 0xffff0000, v53
	v_lshlrev_b32_e32 v50, 16, v54
	v_and_b32_e32 v54, 0xffff0000, v54
	v_lshlrev_b32_e32 v51, 16, v55
	v_and_b32_e32 v55, 0xffff0000, v55
	v_mul_f32_e32 v52, v92, v52
	v_mul_f32_e32 v48, v92, v48
	v_mul_f32_e32 v53, v92, v53
	v_mul_f32_e32 v49, v92, v49
	v_mul_f32_e32 v54, v92, v54
	v_mul_f32_e32 v50, v92, v50
	v_mul_f32_e32 v55, v92, v55
	v_mul_f32_e32 v51, v92, v51
	v_cvt_pk_bf16_f32 v52, v48, v52
	v_cvt_pk_bf16_f32 v53, v49, v53
	v_cvt_pk_bf16_f32 v54, v50, v54
	v_cvt_pk_bf16_f32 v55, v51, v55
	s_nop 0
	ds_write_b64 v38, v[52:53] offset:8192
	ds_write_b64 v38, v[54:55] offset:8208
	s_waitcnt vmcnt(6)
	v_lshlrev_b32_e32 v48, 16, v56
	v_and_b32_e32 v56, 0xffff0000, v56
	v_lshlrev_b32_e32 v49, 16, v57
	v_and_b32_e32 v57, 0xffff0000, v57
	v_lshlrev_b32_e32 v50, 16, v58
	v_and_b32_e32 v58, 0xffff0000, v58
	v_lshlrev_b32_e32 v51, 16, v59
	v_and_b32_e32 v59, 0xffff0000, v59
	v_mul_f32_e32 v56, v93, v56
	v_mul_f32_e32 v48, v93, v48
	v_mul_f32_e32 v57, v93, v57
	v_mul_f32_e32 v49, v93, v49
	v_mul_f32_e32 v58, v93, v58
	v_mul_f32_e32 v50, v93, v50
	v_mul_f32_e32 v59, v93, v59
	v_mul_f32_e32 v51, v93, v51
	v_cvt_pk_bf16_f32 v56, v48, v56
	v_cvt_pk_bf16_f32 v57, v49, v57
	v_cvt_pk_bf16_f32 v58, v50, v58
	v_cvt_pk_bf16_f32 v59, v51, v59
	s_nop 0
	ds_write_b64 v38, v[56:57] offset:9216
	ds_write_b64 v38, v[58:59] offset:9232
	s_waitcnt vmcnt(5)
	v_lshlrev_b32_e32 v48, 16, v60
	v_and_b32_e32 v60, 0xffff0000, v60
	v_lshlrev_b32_e32 v49, 16, v61
	v_and_b32_e32 v61, 0xffff0000, v61
	v_lshlrev_b32_e32 v50, 16, v62
	v_and_b32_e32 v62, 0xffff0000, v62
	v_lshlrev_b32_e32 v51, 16, v63
	v_and_b32_e32 v63, 0xffff0000, v63
	v_mul_f32_e32 v60, v94, v60
	v_mul_f32_e32 v48, v94, v48
	v_mul_f32_e32 v61, v94, v61
	v_mul_f32_e32 v49, v94, v49
	v_mul_f32_e32 v62, v94, v62
	v_mul_f32_e32 v50, v94, v50
	v_mul_f32_e32 v63, v94, v63
	v_mul_f32_e32 v51, v94, v51
	v_cvt_pk_bf16_f32 v60, v48, v60
	v_cvt_pk_bf16_f32 v61, v49, v61
	v_cvt_pk_bf16_f32 v62, v50, v62
	v_cvt_pk_bf16_f32 v63, v51, v63
	s_nop 0
	ds_write_b64 v38, v[60:61] offset:10240
	ds_write_b64 v38, v[62:63] offset:10256
	s_waitcnt vmcnt(4)
; __device__ __forceinline__ unsigned pk2(float a, float b) { return pg8::cvt_pk_bf16(a, b); }
; __device__ __forceinline__ void unpack8(const u32x4 w, float (&f)[8]) { f[0] = bf_lo(w.x); f[1] = bf_hi(w.x); f[2] = bf_lo(w.y); f[3] = bf_hi(w.y); f[4] = bf_lo(w.z); f[5] = bf_hi(w.z); f[6] = bf_lo(w.w); f[7] = bf_hi(w.w); }
; __device__ __forceinline__ void phase_prep(const Args& a, PG8_LAS unsigned char* lds) {
;     ...
; #pragma unroll 4
;             for (int k = 0; k < 16; ++k) { const int pidx = lane + 64 * k, i = pidx >> 4, pc = pidx & 15, aa = pc & 3, c32 = (pc >> 2) * 32;
;                 float f[8]; unpack8(*(const u32x4*)(qbase + (size_t)i * 512 + pc * 8), f); const float e = sE[i];
;                 u32x2 lo, hi; lo.x = pk2(f[0] * e, f[1] * e); lo.y = pk2(f[2] * e, f[3] * e); hi.x = pk2(f[4] * e, f[5] * e); hi.y = pk2(f[6] * e, f[7] * e);
;                 *(u32x2*)(qgp + i * 128 + c32 + 8 * ((2 * aa) & 3) + 4 * (aa >> 1)) = lo;
;                 *(u32x2*)(qgp + i * 128 + c32 + 8 * ((2 * aa + 1) & 3) + 4 * (aa >> 1)) = hi; }
	v_lshlrev_b32_e32 v48, 16, v64
	v_and_b32_e32 v64, 0xffff0000, v64
	v_lshlrev_b32_e32 v49, 16, v65
	v_and_b32_e32 v65, 0xffff0000, v65
	v_lshlrev_b32_e32 v50, 16, v66
	v_and_b32_e32 v66, 0xffff0000, v66
	v_lshlrev_b32_e32 v51, 16, v67
	v_and_b32_e32 v67, 0xffff0000, v67
	v_mul_f32_e32 v64, v95, v64
	v_mul_f32_e32 v48, v95, v48
	v_mul_f32_e32 v65, v95, v65
	v_mul_f32_e32 v49, v95, v49
	v_mul_f32_e32 v66, v95, v66
	v_mul_f32_e32 v50, v95, v50
	v_mul_f32_e32 v67, v95, v67
	v_mul_f32_e32 v51, v95, v51
	v_cvt_pk_bf16_f32 v64, v48, v64
	v_cvt_pk_bf16_f32 v65, v49, v65
	v_cvt_pk_bf16_f32 v66, v50, v66
	v_cvt_pk_bf16_f32 v67, v51, v67
	s_nop 0
	ds_write_b64 v38, v[64:65] offset:11264
	ds_write_b64 v38, v[66:67] offset:11280
	s_waitcnt vmcnt(3)
	v_lshlrev_b32_e32 v48, 16, v68
	v_and_b32_e32 v68, 0xffff0000, v68
	v_lshlrev_b32_e32 v49, 16, v69
	v_and_b32_e32 v69, 0xffff0000, v69
	v_lshlrev_b32_e32 v50, 16, v70
	v_and_b32_e32 v70, 0xffff0000, v70
	v_lshlrev_b32_e32 v51, 16, v71
	v_and_b32_e32 v71, 0xffff0000, v71
	v_mul_f32_e32 v68, v44, v68
	v_mul_f32_e32 v48, v44, v48
	v_mul_f32_e32 v69, v44, v69
	v_mul_f32_e32 v49, v44, v49
	v_mul_f32_e32 v70, v44, v70
	v_mul_f32_e32 v50, v44, v50
	v_mul_f32_e32 v71, v44, v71
	v_mul_f32_e32 v51, v44, v51
	v_cvt_pk_bf16_f32 v68, v48, v68
	v_cvt_pk_bf16_f32 v69, v49, v69
	v_cvt_pk_bf16_f32 v70, v50, v70
	v_cvt_pk_bf16_f32 v71, v51, v71
	s_nop 0
	ds_write_b64 v38, v[68:69] offset:12288
	ds_write_b64 v38, v[70:71] offset:12304
	s_waitcnt vmcnt(2)
	v_lshlrev_b32_e32 v48, 16, v72
	v_and_b32_e32 v72, 0xffff0000, v72
	v_lshlrev_b32_e32 v49, 16, v73
	v_and_b32_e32 v73, 0xffff0000, v73
	v_lshlrev_b32_e32 v50, 16, v74
	v_and_b32_e32 v74, 0xffff0000, v74
	v_lshlrev_b32_e32 v51, 16, v75
	v_and_b32_e32 v75, 0xffff0000, v75
	v_mul_f32_e32 v72, v45, v72
	v_mul_f32_e32 v48, v45, v48
	v_mul_f32_e32 v73, v45, v73
	v_mul_f32_e32 v49, v45, v49
	v_mul_f32_e32 v74, v45, v74
	v_mul_f32_e32 v50, v45, v50
	v_mul_f32_e32 v75, v45, v75
	v_mul_f32_e32 v51, v45, v51
	v_cvt_pk_bf16_f32 v72, v48, v72
	v_cvt_pk_bf16_f32 v73, v49, v73
	v_cvt_pk_bf16_f32 v74, v50, v74
	v_cvt_pk_bf16_f32 v75, v51, v75
	s_nop 0
	ds_write_b64 v38, v[72:73] offset:13312
	ds_write_b64 v38, v[74:75] offset:13328
	s_waitcnt vmcnt(1)
	v_lshlrev_b32_e32 v48, 16, v76
	v_and_b32_e32 v76, 0xffff0000, v76
	v_lshlrev_b32_e32 v49, 16, v77
	v_and_b32_e32 v77, 0xffff0000, v77
	v_lshlrev_b32_e32 v50, 16, v78
	v_and_b32_e32 v78, 0xffff0000, v78
	v_lshlrev_b32_e32 v51, 16, v79
	v_and_b32_e32 v79, 0xffff0000, v79
	v_mul_f32_e32 v76, v46, v76
	v_mul_f32_e32 v48, v46, v48
	v_mul_f32_e32 v77, v46, v77
	v_mul_f32_e32 v49, v46, v49
	v_mul_f32_e32 v78, v46, v78
	v_mul_f32_e32 v50, v46, v50
	v_mul_f32_e32 v79, v46, v79
	v_mul_f32_e32 v51, v46, v51
	v_cvt_pk_bf16_f32 v76, v48, v76
	v_cvt_pk_bf16_f32 v77, v49, v77
	v_cvt_pk_bf16_f32 v78, v50, v78
	v_cvt_pk_bf16_f32 v79, v51, v79
	s_nop 0
	ds_write_b64 v38, v[76:77] offset:14336
	ds_write_b64 v38, v[78:79] offset:14352
	s_waitcnt vmcnt(0)
	v_lshlrev_b32_e32 v48, 16, v80
	v_and_b32_e32 v80, 0xffff0000, v80
	v_lshlrev_b32_e32 v49, 16, v81
	v_and_b32_e32 v81, 0xffff0000, v81
	v_lshlrev_b32_e32 v50, 16, v82
	v_and_b32_e32 v82, 0xffff0000, v82
	v_lshlrev_b32_e32 v51, 16, v83
	v_and_b32_e32 v83, 0xffff0000, v83
	v_mul_f32_e32 v80, v47, v80
	v_mul_f32_e32 v48, v47, v48
	v_mul_f32_e32 v81, v47, v81
	v_mul_f32_e32 v49, v47, v49
	v_mul_f32_e32 v82, v47, v82
	v_mul_f32_e32 v50, v47, v50
	v_mul_f32_e32 v83, v47, v83
	v_mul_f32_e32 v51, v47, v51
	v_cvt_pk_bf16_f32 v80, v48, v80
	v_cvt_pk_bf16_f32 v81, v49, v81
	v_cvt_pk_bf16_f32 v82, v50, v82
	v_cvt_pk_bf16_f32 v83, v51, v83
	s_nop 0
	ds_write_b64 v38, v[80:81] offset:15360
	ds_write_b64 v38, v[82:83] offset:15376
	ds_read_b128 v[52:55], v39
	ds_read_b128 v[56:59], v39 offset:1024
	ds_read_b128 v[60:63], v39 offset:2048
	ds_read_b128 v[64:67], v39 offset:3072
	ds_read_b128 v[68:71], v39 offset:4096
	ds_read_b128 v[72:75], v39 offset:5120
	ds_read_b128 v[76:79], v39 offset:6144
	ds_read_b128 v[80:83], v39 offset:7168
	s_waitcnt lgkmcnt(0)
	global_store_dwordx4 v[42:43], v[52:55], off
	global_store_dwordx4 v[42:43], v[56:59], off offset:1024
	global_store_dwordx4 v[42:43], v[60:63], off offset:2048
	global_store_dwordx4 v[42:43], v[64:67], off offset:3072
	v_add_co_u32_e32 v42, vcc, 0x1000, v42
	s_nop 1
	v_addc_co_u32_e32 v43, vcc, 0, v43, vcc
	global_store_dwordx4 v[42:43], v[68:71], off
	global_store_dwordx4 v[42:43], v[72:75], off offset:1024
	global_store_dwordx4 v[42:43], v[76:79], off offset:2048
	global_store_dwordx4 v[42:43], v[80:83], off offset:3072
	v_add_co_u32_e32 v42, vcc, 0x1000, v42
	s_nop 1
	v_addc_co_u32_e32 v43, vcc, 0, v43, vcc
	ds_read_b128 v[52:55], v39 offset:8192
	ds_read_b128 v[56:59], v39 offset:9216
	ds_read_b128 v[60:63], v39 offset:10240
	ds_read_b128 v[64:67], v39 offset:11264
	ds_read_b128 v[68:71], v39 offset:12288
	ds_read_b128 v[72:75], v39 offset:13312
	ds_read_b128 v[76:79], v39 offset:14336
	ds_read_b128 v[80:83], v39 offset:15360
	s_waitcnt lgkmcnt(0)
	global_store_dwordx4 v[42:43], v[52:55], off
	global_store_dwordx4 v[42:43], v[56:59], off offset:1024
	global_store_dwordx4 v[42:43], v[60:63], off offset:2048
	global_store_dwordx4 v[42:43], v[64:67], off offset:3072
	v_add_co_u32_e32 v42, vcc, 0x1000, v42
	s_nop 1
	v_addc_co_u32_e32 v43, vcc, 0, v43, vcc
	global_store_dwordx4 v[42:43], v[68:71], off
	global_store_dwordx4 v[42:43], v[72:75], off offset:1024
	global_store_dwordx4 v[42:43], v[76:79], off offset:2048
	global_store_dwordx4 v[42:43], v[80:83], off offset:3072
